# grid syncs 2..14: XCD-hierarchical barrier (HW_REG_XCC_ID, one L2 writeback per XCD, per-XCD release words); flat counter fallback if grid != 256
# speedup vs baseline: 1.0175x; 1.0110x over previous
; DI int my_tid() { int t = threadIdx.x; asm volatile("" : "+v"(t)); return t; }
; DI void phase_prep(PRef p) {
;   const int tid0 = my_tid();
;   const int gtid = blockIdx.x * 512 + tid0, gthreads = gridDim.x * 512;
;   char* ws = p.ws;
;   for (int j = 0; j < 2; j++) {
.LBB0_845:
	v_mov_b32_e32 v8, v196
	s_waitcnt lgkmcnt(0)
	s_load_dwordx8 s[20:27], s[0:1], 0x20
	s_load_dwordx2 s[4:5], s[0:1], 0xb0
	s_mov_b32 s65, s52
	s_mov_b32 s52, s62
	s_mov_b32 s62, s54
	s_waitcnt lgkmcnt(0)
	s_cmp_lg_u64 s[20:21], 0
	s_cselect_b64 s[18:19], -1, 0
	s_add_u32 s28, s4, 0x800000
	s_addc_u32 s29, s5, 0
	v_readlane_b32 s14, v226, 0
	s_cmp_lg_u32 s14, 0
	s_cbranch_scc1 .Lgb_init_skip
	v_lshlrev_b32_e32 v0, 4, v196
	v_mov_b32_e32 v2, 0
	v_mov_b32_e32 v3, 0
	v_mov_b32_e32 v4, 0
	v_mov_b32_e32 v5, 0
	v_add_u32_e32 v0, 0x25d6000, v0
	global_store_dwordx4 v0, v[2:5], s[4:5]

; __global__ void __launch_bounds__(512, 2) mega(Params p_, int ph_lo, int ph_hi, int coop) {
;     ...
;     if (coop && ph + 1 < ph_hi) cg::this_grid().sync();
.LBB0_1073:
	s_cmp_lt_u32 s12, 2
	s_cbranch_scc1 .Lgb_cg_path
	v_readlane_b32 s8, v226, 42
	v_readlane_b32 s9, v226, 43
	s_add_i32 s13, s12, -1
	s_getreg_b32 s14, hwreg(HW_REG_XCC_ID, 0, 4)
	s_load_dword s15, s[8:9], 0xc8
	s_load_dwordx2 s[8:9], s[8:9], 0xb0
	s_and_b32 s14, s14, 7
	s_lshl_b32 s14, s14, 8
	v_mov_b32_e32 v1, 1
	s_waitcnt lgkmcnt(0)
	s_add_u32 s8, s8, 0x25d6000
	s_addc_u32 s9, s9, 0
	s_cmp_lg_u32 s15, 0x100
	s_cbranch_scc1 .Lgb_flat
	s_add_u32 s10, s8, s14
	s_addc_u32 s11, s9, 0
	global_atomic_add v2, v129, v1, s[10:11] offset:256 sc0 sc1
	s_waitcnt vmcnt(0)
	v_readfirstlane_b32 s14, v2
	s_lshl_b32 s15, s13, 5
	s_add_u32 s14, s14, 1
	s_cmp_eq_u32 s14, s15
	s_cbranch_scc0 .Lgb_follower
	buffer_wbl2 sc1
	s_waitcnt vmcnt(0)
	global_atomic_add v2, v129, v1, s[8:9] sc0 sc1
	s_waitcnt vmcnt(0)
	v_readfirstlane_b32 s14, v2
	s_lshl_b32 s15, s13, 3
	s_add_u32 s14, s14, 1
	s_cmp_eq_u32 s14, s15
	s_cbranch_scc0 .Lgb_wait_top
	global_atomic_add v129, v1, s[8:9] offset:128 sc1
	s_branch .Lgb_leader_rel
.Lgb_wait_top:
	s_mov_b32 s14, 0
.Lgb_poll_top:
	s_sleep 1
	global_load_dword v2, v129, s[8:9] offset:128 sc1
	s_add_u32 s14, s14, 1
	s_waitcnt vmcnt(0)
	v_cmp_gt_u32_e32 vcc, s13, v2
	s_and_b64 vcc, exec, vcc
	s_cbranch_vccz .Lgb_leader_rel
	s_cmp_lt_u32 s14, 0x20000
	s_cbranch_scc1 .Lgb_poll_top
.Lgb_leader_rel:
	buffer_inv sc1
	global_atomic_add v129, v1, s[10:11] offset:2304 sc1
	s_waitcnt vmcnt(0)
	s_branch .Lgb_to2

; __global__ void __launch_bounds__(512, 2) mega(Params p_, int ph_lo, int ph_hi, int coop) {
;     ...
;     if (coop && ph + 1 < ph_hi) cg::this_grid().sync();
.Lgb_poll_x:
	s_sleep 1
	global_load_dword v2, v129, s[10:11] offset:2304 sc1
	s_add_u32 s14, s14, 1
	s_waitcnt vmcnt(0)
	v_cmp_gt_u32_e32 vcc, s13, v2
	s_and_b64 vcc, exec, vcc
	s_cbranch_vccz .Lgb_fol_done
	s_cmp_lt_u32 s14, 0x20000
	s_cbranch_scc1 .Lgb_poll_x

; __global__ void __launch_bounds__(512, 2) mega(Params p_, int ph_lo, int ph_hi, int coop) {
;     ...
;     if (coop && ph + 1 < ph_hi) cg::this_grid().sync();
.Lgb_flat:
	buffer_wbl2 sc1
	s_waitcnt vmcnt(0)
	s_mul_i32 s13, s13, s15
	global_atomic_add v129, v1, s[8:9] offset:3072 sc1
	s_mov_b32 s14, 0
.Lgb_poll_flat:
	s_sleep 1
	global_load_dword v2, v129, s[8:9] offset:3072 sc1
	s_add_u32 s14, s14, 1
	s_waitcnt vmcnt(0)
	v_cmp_gt_u32_e32 vcc, s13, v2
	s_and_b64 vcc, exec, vcc
	s_cbranch_vccz .Lgb_fol_done
	s_cmp_lt_u32 s14, 0x20000
	s_cbranch_scc1 .Lgb_poll_flat
	s_branch .Lgb_fol_done
